# P12 row pass: F loads (written by the previous phase) without the non-temporal hint
# baseline (speedup 1.0000x reference)
; __device__ __forceinline__ f32x4 up4(u32x2 w) { return (f32x4){bf_lo(w.x), bf_hi(w.x), bf_lo(w.y), bf_hi(w.y)}; }
; template <bool DRYR = false>
; __device__ __forceinline__ void row_pass2(const Args& a, int row_lo, int row_hi, int gw, int NGW, int lane) {
;     ...
;     for (int r0 = row_lo + 2 * gw; r0 < row_hi; r0 += 2 * NGW) {
;         f32x4 xv[2][4]; u32x2 fv[2][4]; float rs[2];
; #pragma unroll
;         for (int r = 0; r < 2; ++r) { const int row = (r0 + r < row_hi) ? r0 + r : r0; rs[r] = rss[row];
;             const f32x4* xo = (const f32x4*)(XO + (size_t)row * DM) + lane; const u32x2* fr = (const u32x2*)(F + (size_t)row * DM) + lane;
; #pragma unroll
;             for (int j = 0; j < 4; ++j) { xv[r][j] = xo[64 * j]; fv[r][j] = fr[64 * j]; } }
; #pragma unroll
;         for (int r = 0; r < 2; ++r) { const int row = r0 + r; if (row >= row_hi) break;
;             const float rstd = rsqrtf(rs[r] * (1.f / DM) + EPS); f32x4* xo = (f32x4*)(XO + (size_t)row * DM) + lane;
; #pragma unroll
;             for (int j = 0; j < 4; ++j) { const f32x4 o = xv[r][j] + up4(fv[r][j]) * rstd * gp[j]; if (!DRYR || o[0] == 123.456f) xo[64 * j] = o; } }
.Lxo_loop:
	global_load_dwordx2 v[80:81], v145, s[16:17]
	global_load_dwordx2 v[82:83], v145, s[18:19]
	global_load_dwordx2 v[48:49], v146, s[24:25] nt
	global_load_dwordx2 v[50:51], v146, s[24:25] offset:512 nt
	global_load_dwordx2 v[52:53], v146, s[24:25] offset:1024 nt
	global_load_dwordx2 v[54:55], v146, s[24:25] offset:1536 nt
	global_load_dwordx4 v[16:19], v144, s[20:21] nt
	global_load_dwordx4 v[20:23], v144, s[20:21] offset:1024 nt
	global_load_dwordx4 v[24:27], v144, s[20:21] offset:2048 nt
	global_load_dwordx4 v[28:31], v144, s[20:21] offset:3072 nt
	global_load_dwordx2 v[64:65], v146, s[26:27]
	global_load_dwordx2 v[66:67], v146, s[26:27] offset:512
	global_load_dwordx2 v[68:69], v146, s[26:27] offset:1024
	global_load_dwordx2 v[70:71], v146, s[26:27] offset:1536
	global_load_dwordx2 v[56:57], v146, s[24:25] offset:2048 nt
	global_load_dwordx2 v[58:59], v146, s[24:25] offset:2560 nt
	global_load_dwordx2 v[60:61], v146, s[24:25] offset:3072 nt
	global_load_dwordx2 v[62:63], v146, s[24:25] offset:3584 nt
	global_load_dwordx4 v[32:35], v147, s[20:21] nt
	global_load_dwordx4 v[36:39], v147, s[20:21] offset:1024 nt
	global_load_dwordx4 v[40:43], v147, s[20:21] offset:2048 nt
	global_load_dwordx4 v[44:47], v147, s[20:21] offset:3072 nt
	global_load_dwordx2 v[72:73], v146, s[26:27] offset:2048
	global_load_dwordx2 v[74:75], v146, s[26:27] offset:2560
	global_load_dwordx2 v[76:77], v146, s[26:27] offset:3072
	global_load_dwordx2 v[78:79], v146, s[26:27] offset:3584
	s_waitcnt vmcnt(12)
	v_fmamk_f32 v104, v80, 0x3a800000, v116
	v_mul_f32_e32 v105, 0x4b800000, v104
	v_cmp_gt_f32_e32 vcc, s3, v104
	s_nop 1
	v_cndmask_b32_e32 v104, v104, v105, vcc
	v_rsq_f32_e32 v104, v104
	s_nop 0
	v_mul_f32_e32 v105, 0x45800000, v104
	v_cndmask_b32_e32 v104, v104, v105, vcc
	v_fmamk_f32 v106, v82, 0x3a800000, v116
	v_mul_f32_e32 v107, 0x4b800000, v106
	v_cmp_gt_f32_e32 vcc, s3, v106
	s_nop 1
	v_cndmask_b32_e32 v106, v106, v107, vcc
	v_rsq_f32_e32 v106, v106
	s_nop 0
	v_mul_f32_e32 v107, 0x45800000, v106
	v_cndmask_b32_e32 v106, v106, v107, vcc
	v_lshlrev_b32_e32 v120, 16, v48
	v_and_b32_e32 v121, 0xffff0000, v48
	v_lshlrev_b32_e32 v122, 16, v49
	v_and_b32_e32 v123, 0xffff0000, v49
	v_lshlrev_b32_e32 v150, 16, v64
	v_and_b32_e32 v151, 0xffff0000, v64
	v_lshlrev_b32_e32 v152, 16, v65
	v_and_b32_e32 v153, 0xffff0000, v65
	v_pk_mul_f32 v[120:121], v[104:105], v[120:121] op_sel_hi:[0,1]
	v_pk_mul_f32 v[122:123], v[104:105], v[122:123] op_sel_hi:[0,1]
	v_pk_mul_f32 v[150:151], v[106:107], v[150:151] op_sel_hi:[0,1]
	v_pk_mul_f32 v[152:153], v[106:107], v[152:153] op_sel_hi:[0,1]
	v_pk_fma_f32 v[16:17], v[84:85], v[120:121], v[16:17]
	v_pk_fma_f32 v[18:19], v[86:87], v[122:123], v[18:19]
	v_pk_fma_f32 v[16:17], v[0:1], v[150:151], v[16:17]
	v_pk_fma_f32 v[18:19], v[2:3], v[152:153], v[18:19]
	v_lshlrev_b32_e32 v124, 16, v50
	v_and_b32_e32 v125, 0xffff0000, v50
	v_lshlrev_b32_e32 v126, 16, v51
	v_and_b32_e32 v127, 0xffff0000, v51
	v_lshlrev_b32_e32 v154, 16, v66
	v_and_b32_e32 v155, 0xffff0000, v66
	v_lshlrev_b32_e32 v156, 16, v67
	v_and_b32_e32 v157, 0xffff0000, v67
	v_pk_mul_f32 v[124:125], v[104:105], v[124:125] op_sel_hi:[0,1]
	v_pk_mul_f32 v[126:127], v[104:105], v[126:127] op_sel_hi:[0,1]
	v_pk_mul_f32 v[154:155], v[106:107], v[154:155] op_sel_hi:[0,1]
	v_pk_mul_f32 v[156:157], v[106:107], v[156:157] op_sel_hi:[0,1]
	v_pk_fma_f32 v[20:21], v[88:89], v[124:125], v[20:21]
	v_pk_fma_f32 v[22:23], v[90:91], v[126:127], v[22:23]
	v_pk_fma_f32 v[20:21], v[4:5], v[154:155], v[20:21]
	v_pk_fma_f32 v[22:23], v[6:7], v[156:157], v[22:23]
	v_lshlrev_b32_e32 v128, 16, v52
	v_and_b32_e32 v129, 0xffff0000, v52
	v_lshlrev_b32_e32 v130, 16, v53
	v_and_b32_e32 v131, 0xffff0000, v53
	v_lshlrev_b32_e32 v158, 16, v68
	v_and_b32_e32 v159, 0xffff0000, v68
	v_lshlrev_b32_e32 v160, 16, v69
	v_and_b32_e32 v161, 0xffff0000, v69
	v_pk_mul_f32 v[128:129], v[104:105], v[128:129] op_sel_hi:[0,1]
	v_pk_mul_f32 v[130:131], v[104:105], v[130:131] op_sel_hi:[0,1]
	v_pk_mul_f32 v[158:159], v[106:107], v[158:159] op_sel_hi:[0,1]
	v_pk_mul_f32 v[160:161], v[106:107], v[160:161] op_sel_hi:[0,1]
	v_pk_fma_f32 v[24:25], v[92:93], v[128:129], v[24:25]
	v_pk_fma_f32 v[26:27], v[94:95], v[130:131], v[26:27]
	v_pk_fma_f32 v[24:25], v[8:9], v[158:159], v[24:25]
	v_pk_fma_f32 v[26:27], v[10:11], v[160:161], v[26:27]
	v_lshlrev_b32_e32 v132, 16, v54
	v_and_b32_e32 v133, 0xffff0000, v54
	v_lshlrev_b32_e32 v134, 16, v55
	v_and_b32_e32 v135, 0xffff0000, v55
	v_lshlrev_b32_e32 v162, 16, v70
	v_and_b32_e32 v163, 0xffff0000, v70
	v_lshlrev_b32_e32 v164, 16, v71
	v_and_b32_e32 v165, 0xffff0000, v71
	v_pk_mul_f32 v[132:133], v[104:105], v[132:133] op_sel_hi:[0,1]
	v_pk_mul_f32 v[134:135], v[104:105], v[134:135] op_sel_hi:[0,1]
	v_pk_mul_f32 v[162:163], v[106:107], v[162:163] op_sel_hi:[0,1]
	v_pk_mul_f32 v[164:165], v[106:107], v[164:165] op_sel_hi:[0,1]
	v_pk_fma_f32 v[28:29], v[96:97], v[132:133], v[28:29]
	v_pk_fma_f32 v[30:31], v[98:99], v[134:135], v[30:31]
	v_pk_fma_f32 v[28:29], v[12:13], v[162:163], v[28:29]
	v_pk_fma_f32 v[30:31], v[14:15], v[164:165], v[30:31]
	global_store_dwordx4 v144, v[16:19], s[22:23] nt
	global_store_dwordx4 v144, v[20:23], s[22:23] offset:1024 nt
	global_store_dwordx4 v144, v[24:27], s[22:23] offset:2048 nt
	global_store_dwordx4 v144, v[28:31], s[22:23] offset:3072 nt
	s_waitcnt vmcnt(4)
; __device__ __forceinline__ f32x4 up4(u32x2 w) { return (f32x4){bf_lo(w.x), bf_hi(w.x), bf_lo(w.y), bf_hi(w.y)}; }
; template <bool DRYR = false>
; __device__ __forceinline__ void row_pass2(const Args& a, int row_lo, int row_hi, int gw, int NGW, int lane) {
;     ...
; #pragma unroll
;         for (int r = 0; r < 2; ++r) { const int row = r0 + r; if (row >= row_hi) break;
;             const float rstd = rsqrtf(rs[r] * (1.f / DM) + EPS); f32x4* xo = (f32x4*)(XO + (size_t)row * DM) + lane;
; #pragma unroll
;             for (int j = 0; j < 4; ++j) { const f32x4 o = xv[r][j] + up4(fv[r][j]) * rstd * gp[j]; if (!DRYR || o[0] == 123.456f) xo[64 * j] = o; } }
;     }
	v_fmamk_f32 v104, v81, 0x3a800000, v116
	v_mul_f32_e32 v105, 0x4b800000, v104
	v_cmp_gt_f32_e32 vcc, s3, v104
	s_nop 1
	v_cndmask_b32_e32 v104, v104, v105, vcc
	v_rsq_f32_e32 v104, v104
	s_nop 0
	v_mul_f32_e32 v105, 0x45800000, v104
	v_cndmask_b32_e32 v104, v104, v105, vcc
	v_fmamk_f32 v106, v83, 0x3a800000, v116
	v_mul_f32_e32 v107, 0x4b800000, v106
	v_cmp_gt_f32_e32 vcc, s3, v106
	s_nop 1
	v_cndmask_b32_e32 v106, v106, v107, vcc
	v_rsq_f32_e32 v106, v106
	s_nop 0
	v_mul_f32_e32 v107, 0x45800000, v106
	v_cndmask_b32_e32 v106, v106, v107, vcc
	v_lshlrev_b32_e32 v120, 16, v56
	v_and_b32_e32 v121, 0xffff0000, v56
	v_lshlrev_b32_e32 v122, 16, v57
	v_and_b32_e32 v123, 0xffff0000, v57
	v_lshlrev_b32_e32 v150, 16, v72
	v_and_b32_e32 v151, 0xffff0000, v72
	v_lshlrev_b32_e32 v152, 16, v73
	v_and_b32_e32 v153, 0xffff0000, v73
	v_pk_mul_f32 v[120:121], v[104:105], v[120:121] op_sel_hi:[0,1]
	v_pk_mul_f32 v[122:123], v[104:105], v[122:123] op_sel_hi:[0,1]
	v_pk_mul_f32 v[150:151], v[106:107], v[150:151] op_sel_hi:[0,1]
	v_pk_mul_f32 v[152:153], v[106:107], v[152:153] op_sel_hi:[0,1]
	v_pk_fma_f32 v[32:33], v[84:85], v[120:121], v[32:33]
	v_pk_fma_f32 v[34:35], v[86:87], v[122:123], v[34:35]
	v_pk_fma_f32 v[32:33], v[0:1], v[150:151], v[32:33]
	v_pk_fma_f32 v[34:35], v[2:3], v[152:153], v[34:35]
	v_lshlrev_b32_e32 v124, 16, v58
	v_and_b32_e32 v125, 0xffff0000, v58
	v_lshlrev_b32_e32 v126, 16, v59
	v_and_b32_e32 v127, 0xffff0000, v59
	v_lshlrev_b32_e32 v154, 16, v74
	v_and_b32_e32 v155, 0xffff0000, v74
	v_lshlrev_b32_e32 v156, 16, v75
	v_and_b32_e32 v157, 0xffff0000, v75
	v_pk_mul_f32 v[124:125], v[104:105], v[124:125] op_sel_hi:[0,1]
	v_pk_mul_f32 v[126:127], v[104:105], v[126:127] op_sel_hi:[0,1]
	v_pk_mul_f32 v[154:155], v[106:107], v[154:155] op_sel_hi:[0,1]
	v_pk_mul_f32 v[156:157], v[106:107], v[156:157] op_sel_hi:[0,1]
	v_pk_fma_f32 v[36:37], v[88:89], v[124:125], v[36:37]
	v_pk_fma_f32 v[38:39], v[90:91], v[126:127], v[38:39]
	v_pk_fma_f32 v[36:37], v[4:5], v[154:155], v[36:37]
	v_pk_fma_f32 v[38:39], v[6:7], v[156:157], v[38:39]
	v_lshlrev_b32_e32 v128, 16, v60
	v_and_b32_e32 v129, 0xffff0000, v60
	v_lshlrev_b32_e32 v130, 16, v61
	v_and_b32_e32 v131, 0xffff0000, v61
	v_lshlrev_b32_e32 v158, 16, v76
	v_and_b32_e32 v159, 0xffff0000, v76
	v_lshlrev_b32_e32 v160, 16, v77
	v_and_b32_e32 v161, 0xffff0000, v77
	v_pk_mul_f32 v[128:129], v[104:105], v[128:129] op_sel_hi:[0,1]
	v_pk_mul_f32 v[130:131], v[104:105], v[130:131] op_sel_hi:[0,1]
	v_pk_mul_f32 v[158:159], v[106:107], v[158:159] op_sel_hi:[0,1]
	v_pk_mul_f32 v[160:161], v[106:107], v[160:161] op_sel_hi:[0,1]
	v_pk_fma_f32 v[40:41], v[92:93], v[128:129], v[40:41]
	v_pk_fma_f32 v[42:43], v[94:95], v[130:131], v[42:43]
	v_pk_fma_f32 v[40:41], v[8:9], v[158:159], v[40:41]
	v_pk_fma_f32 v[42:43], v[10:11], v[160:161], v[42:43]
	v_lshlrev_b32_e32 v132, 16, v62
	v_and_b32_e32 v133, 0xffff0000, v62
	v_lshlrev_b32_e32 v134, 16, v63
	v_and_b32_e32 v135, 0xffff0000, v63
	v_lshlrev_b32_e32 v162, 16, v78
	v_and_b32_e32 v163, 0xffff0000, v78
	v_lshlrev_b32_e32 v164, 16, v79
	v_and_b32_e32 v165, 0xffff0000, v79
	v_pk_mul_f32 v[132:133], v[104:105], v[132:133] op_sel_hi:[0,1]
	v_pk_mul_f32 v[134:135], v[104:105], v[134:135] op_sel_hi:[0,1]
	v_pk_mul_f32 v[162:163], v[106:107], v[162:163] op_sel_hi:[0,1]
	v_pk_mul_f32 v[164:165], v[106:107], v[164:165] op_sel_hi:[0,1]
	v_pk_fma_f32 v[44:45], v[96:97], v[132:133], v[44:45]
	v_pk_fma_f32 v[46:47], v[98:99], v[134:135], v[46:47]
	v_pk_fma_f32 v[44:45], v[12:13], v[162:163], v[44:45]
	v_pk_fma_f32 v[46:47], v[14:15], v[164:165], v[46:47]
	global_store_dwordx4 v147, v[32:35], s[22:23] nt
	global_store_dwordx4 v147, v[36:39], s[22:23] offset:1024 nt
	global_store_dwordx4 v147, v[40:43], s[22:23] offset:2048 nt
	global_store_dwordx4 v147, v[44:47], s[22:23] offset:3072 nt
	s_add_i32 s0, s0, s4
	s_add_u32 s20, s20, s98
	s_addc_u32 s21, s21, 0
	s_add_u32 s22, s22, s98
	s_addc_u32 s23, s23, 0
	s_add_u32 s24, s24, s99
	s_addc_u32 s25, s25, 0
	s_add_u32 s26, s26, s99
	s_addc_u32 s27, s27, 0
	s_add_u32 s16, s16, s100
	s_addc_u32 s17, s17, 0
	s_add_u32 s18, s18, s100
	s_addc_u32 s19, s19, 0
	s_cmpk_gt_i32 s0, 0x3fff
	s_cbranch_scc0 .Lxo_loop
